# P4 group-A epilogue: sink logits requested first in the epilogue; their wait leaves the z loads in flight
# speedup vs baseline: 1.0012x; 1.0012x over previous
.LBB0_682:
	s_and_b64 vcc, exec, s[26:27]
	s_cbranch_vccz .Lsk_skip
	s_add_i32 s76, s65, s53
	s_ashr_i32 s77, s76, 31
	s_lshl_b64 s[76:77], s[76:77], 2
	s_add_u32 s76, s82, s76
	s_addc_u32 s77, s83, s77
	global_load_dwordx2 v[238:239], v2, s[76:77]

.LBB0_684:
	s_nop 0
	v_mov_b32_e32 v4, v180
	v_mov_b32_e32 v5, v181
	s_andn2_b64 vcc, exec, s[26:27]
	v_permlane32_swap_b32_e32 v180, v4
	v_permlane32_swap_b32_e32 v181, v5
	v_pk_add_f32 v[4:5], v[180:181], v[4:5]
	s_cbranch_vccnz .LBB0_686
	s_lshl_b32 s0, s65, 2
	s_add_i32 s0, s0, 0
	s_add_i32 s0, s0, 0x24200
	v_mov_b32_e32 v3, s0
	ds_read_b64 v[8:9], v3
	s_waitcnt vmcnt(8) lgkmcnt(0)
	v_mov_b32_e32 v6, v238
	v_mov_b32_e32 v7, v239
	v_sub_f32_e32 v3, v6, v8
	v_sub_f32_e32 v6, v7, v9
	v_mul_f32_e32 v3, 0x3fb8aa3b, v3
	v_mul_f32_e32 v7, 0x3fb8aa3b, v6
	v_exp_f32_e32 v6, v3
	v_exp_f32_e32 v7, v7
	s_nop 0
	v_pk_add_f32 v[4:5], v[4:5], v[6:7]
